# P3 prompt-unit epilogue fully in permuted lane order (O and 1/l permuted in place, SU loads and OAB stores with permuted addresses), on top of v023
# speedup vs baseline: 1.0055x; 1.0007x over previous
; template <int MODE, bool SAMPLE>
; DEVI void attn_unit(const Params& p, const int b, const int h, const int qt, unsigned char* smem) {
;     ...
;     if (active) {
;         const bf16_t* SU = (const bf16_t*)(p.ws + (MODE == 0 ? W_SUA : W_SUB));
;         bf16_t* OAB = (bf16_t*)(p.ws + W_OAB);
.LBB0_892:
	s_or_b64 exec, exec, s[4:5]
	v_and_b32_e32 v250, 63, v203
	v_and_b32_e32 v251, 3, v250
	v_lshrrev_b32_e32 v252, 4, v250
	v_bfe_u32 v253, v250, 2, 2
	v_lshl_add_u32 v252, v252, 2, v253
	v_lshl_add_u32 v250, v251, 4, v252
	v_lshlrev_b32_e32 v250, 2, v250
	v_or_b32_e32 v36, s60, v73
	v_lshlrev_b64 v[32:33], 1, v[62:63]
	v_lshl_add_u64 v[34:35], s[14:15], 0, v[32:33]
	v_lshlrev_b32_e32 v64, 1, v36
	v_lshl_add_u64 v[34:35], v[34:35], 0, v[64:65]
	v_lshlrev_b64 v[42:43], 1, v[60:61]
	s_barrier
; DEVI unsigned pk_bf16(float lo, float hi) { const f32x2_t v = {lo, hi}; const bf16x2_t b = __builtin_convertvector(v, bf16x2_t); return __builtin_bit_cast(unsigned, b); }
; DEVI float bf_lo(unsigned u) { return __uint_as_float(u << 16); }
; DEVI float bf_hi(unsigned u) { return __uint_as_float(u & 0xffff0000u); }
; DEVI float shx(float v, int m) { return __shfl_xor(v, m); }
; template <int MODE, bool SAMPLE>
; DEVI void attn_unit(const Params& p, const int b, const int h, const int qt, unsigned char* smem) {
;     ...
; #pragma unroll
;         for (int j = 0; j < 2; ++j) {
;             float inv = 1.0f;
;             if (MODE == 0) { float l = st_l[j]; l += shx(l, 16); l += shx(l, 32); inv = (l > 0.f) ? __builtin_amdgcn_rcpf(l) : 0.f; }
;             const int tok = tok0 + 16 * j + l15;
; #pragma unroll
;             for (int dt = 0; dt < 4; ++dt) {
;                 const int col = h * 64 + 16 * dt + 4 * g;
;                 const u32x2 su = *(const u32x2*)(SU + (size_t)tok * 512 + col);
;                 f32x4 o = O[dt][j] * inv;
;                 u32x2 ov; ov.x = pk_bf16(o[0] * bf_lo(su.x), o[1] * bf_hi(su.x)); ov.y = pk_bf16(o[2] * bf_lo(su.y), o[3] * bf_hi(su.y));
;                 *(u32x2*)(OAB + (MODE == 0 ? (size_t)0 : (size_t)NTOK * 512) + (size_t)tok * 512 + col) = ov;
;             }
	ds_bpermute_b32 v246, v250, v34
	ds_bpermute_b32 v247, v250, v35
	s_waitcnt lgkmcnt(0)
	global_load_dwordx2 v[36:37], v[246:247], off
	global_load_dwordx2 v[38:39], v[246:247], off offset:32
	global_load_dwordx2 v[40:41], v[246:247], off offset:64
	s_nop 0
	global_load_dwordx2 v[34:35], v[246:247], off offset:96
	v_lshl_add_u64 v[44:45], s[14:15], 0, v[42:43]
	v_cmp_lt_i32_e32 vcc, v49, v48
	v_lshl_add_u64 v[44:45], v[44:45], 0, v[64:65]
	ds_bpermute_b32 v248, v250, v44
	ds_bpermute_b32 v249, v250, v45
	s_waitcnt lgkmcnt(0)
	global_load_dwordx2 v[46:47], v[248:249], off
	global_load_dwordx2 v[52:53], v[248:249], off offset:32
	v_cndmask_b32_e32 v49, v51, v49, vcc
	v_lshlrev_b32_e32 v98, 2, v49
	ds_bpermute_b32 v54, v98, v68
	ds_bpermute_b32 v55, v98, v69
	v_cmp_lt_i32_e32 vcc, v50, v48
	v_lshl_add_u64 v[32:33], s[16:17], 0, v[32:33]
	v_lshl_add_u64 v[32:33], v[32:33], 0, v[64:65]
	v_cndmask_b32_e32 v48, v51, v50, vcc
	v_lshlrev_b32_e32 v99, 2, v48
	s_waitcnt lgkmcnt(0)
	v_pk_add_f32 v[48:49], v[68:69], v[54:55]
	global_load_dwordx2 v[54:55], v[248:249], off offset:64
	ds_bpermute_b32 v50, v99, v48
	global_load_dwordx2 v[44:45], v[248:249], off offset:96
	ds_bpermute_b32 v51, v99, v49
	v_lshl_add_u64 v[42:43], s[16:17], 0, v[42:43]
	s_add_i32 s61, s61, 1
	s_cmp_eq_u32 s61, 4
	s_waitcnt lgkmcnt(0)
	v_pk_add_f32 v[48:49], v[48:49], v[50:51]
	ds_bpermute_b32 v0, v250, v0
	ds_bpermute_b32 v1, v250, v1
	ds_bpermute_b32 v2, v250, v2
	ds_bpermute_b32 v3, v250, v3
	ds_bpermute_b32 v4, v250, v4
	ds_bpermute_b32 v5, v250, v5
	ds_bpermute_b32 v6, v250, v6
	ds_bpermute_b32 v7, v250, v7
	ds_bpermute_b32 v8, v250, v8
	ds_bpermute_b32 v9, v250, v9
	ds_bpermute_b32 v10, v250, v10
	s_waitcnt lgkmcnt(0)
	ds_bpermute_b32 v11, v250, v11
	ds_bpermute_b32 v12, v250, v12
	ds_bpermute_b32 v13, v250, v13
	ds_bpermute_b32 v14, v250, v14
	ds_bpermute_b32 v15, v250, v15
	ds_bpermute_b32 v16, v250, v16
	ds_bpermute_b32 v17, v250, v17
	ds_bpermute_b32 v18, v250, v18
	ds_bpermute_b32 v19, v250, v19
	ds_bpermute_b32 v20, v250, v20
	ds_bpermute_b32 v21, v250, v21
	s_waitcnt lgkmcnt(0)
	ds_bpermute_b32 v22, v250, v22
	ds_bpermute_b32 v23, v250, v23
	ds_bpermute_b32 v24, v250, v24
	ds_bpermute_b32 v25, v250, v25
	ds_bpermute_b32 v26, v250, v26
	ds_bpermute_b32 v27, v250, v27
	ds_bpermute_b32 v28, v250, v28
	ds_bpermute_b32 v29, v250, v29
	ds_bpermute_b32 v30, v250, v30
	ds_bpermute_b32 v31, v250, v31
	s_waitcnt lgkmcnt(0)
	s_nop 0
	v_rcp_f32_e32 v50, v48
	v_rcp_f32_e32 v51, v49
	v_cmp_lt_f32_e32 vcc, 0, v48
	s_waitcnt vmcnt(6)
	v_lshlrev_b32_e32 v56, 16, v38
	v_cndmask_b32_e32 v48, 0, v50, vcc
	ds_bpermute_b32 v48, v250, v48
	s_waitcnt lgkmcnt(0)
	v_cmp_lt_f32_e32 vcc, 0, v49
	v_pk_mul_f32 v[30:31], v[30:31], v[48:49] op_sel_hi:[1,0]
	v_pk_mul_f32 v[28:29], v[28:29], v[48:49] op_sel_hi:[1,0]
	v_pk_mul_f32 v[14:15], v[14:15], v[48:49] op_sel_hi:[1,0]
	v_pk_mul_f32 v[12:13], v[12:13], v[48:49] op_sel_hi:[1,0]
	v_pk_mul_f32 v[26:27], v[26:27], v[48:49] op_sel_hi:[1,0]
	v_pk_mul_f32 v[24:25], v[24:25], v[48:49] op_sel_hi:[1,0]
	v_pk_mul_f32 v[18:19], v[18:19], v[48:49] op_sel_hi:[1,0]
	v_pk_mul_f32 v[16:17], v[16:17], v[48:49] op_sel_hi:[1,0]
	v_lshlrev_b32_e32 v48, 16, v36
	v_and_b32_e32 v49, 0xffff0000, v36
	v_lshlrev_b32_e32 v36, 16, v37
	v_and_b32_e32 v37, 0xffff0000, v37
	v_and_b32_e32 v57, 0xffff0000, v38
	v_lshlrev_b32_e32 v38, 16, v39
	v_and_b32_e32 v39, 0xffff0000, v39
	s_waitcnt vmcnt(5)
	v_lshlrev_b32_e32 v58, 16, v40
	v_and_b32_e32 v59, 0xffff0000, v40
	v_lshlrev_b32_e32 v40, 16, v41
	v_and_b32_e32 v41, 0xffff0000, v41
	s_waitcnt vmcnt(4)
	v_lshlrev_b32_e32 v60, 16, v34
	v_and_b32_e32 v61, 0xffff0000, v34
	v_lshlrev_b32_e32 v34, 16, v35
	v_and_b32_e32 v35, 0xffff0000, v35
	v_pk_mul_f32 v[28:29], v[28:29], v[48:49]
	v_pk_mul_f32 v[30:31], v[30:31], v[36:37]
	v_pk_mul_f32 v[12:13], v[12:13], v[56:57]
	v_pk_mul_f32 v[14:15], v[14:15], v[38:39]
	v_pk_mul_f32 v[24:25], v[24:25], v[58:59]
	v_pk_mul_f32 v[26:27], v[26:27], v[40:41]
	v_cndmask_b32_e32 v50, 0, v51, vcc
	ds_bpermute_b32 v50, v250, v50
	s_waitcnt lgkmcnt(0)
	v_pk_mul_f32 v[16:17], v[16:17], v[60:61]
	v_pk_mul_f32 v[18:19], v[18:19], v[34:35]
	v_cvt_pk_bf16_f32 v28, v28, v29
	v_cvt_pk_bf16_f32 v29, v30, v31
	v_cvt_pk_bf16_f32 v12, v12, v13
	v_cvt_pk_bf16_f32 v13, v14, v15
	v_cvt_pk_bf16_f32 v14, v24, v25
	v_cvt_pk_bf16_f32 v15, v26, v27
	v_pk_mul_f32 v[22:23], v[22:23], v[50:51] op_sel_hi:[1,0]
	v_pk_mul_f32 v[20:21], v[20:21], v[50:51] op_sel_hi:[1,0]
	s_waitcnt vmcnt(3)
	v_lshlrev_b32_e32 v62, 16, v46
	v_cvt_pk_bf16_f32 v16, v16, v17
	v_cvt_pk_bf16_f32 v17, v18, v19
	ds_bpermute_b32 v246, v250, v32
	ds_bpermute_b32 v247, v250, v33
	s_waitcnt lgkmcnt(0)
	global_store_dwordx2 v[246:247], v[28:29], off
	global_store_dwordx2 v[246:247], v[12:13], off offset:32
	global_store_dwordx2 v[246:247], v[14:15], off offset:64
	global_store_dwordx2 v[246:247], v[16:17], off offset:96
	v_and_b32_e32 v63, 0xffff0000, v46
	v_lshlrev_b32_e32 v14, 16, v47
	v_and_b32_e32 v15, 0xffff0000, v47
	v_pk_mul_f32 v[12:13], v[20:21], v[62:63]
	v_pk_mul_f32 v[14:15], v[22:23], v[14:15]
	v_cvt_pk_bf16_f32 v12, v12, v13
	v_cvt_pk_bf16_f32 v13, v14, v15
	v_lshl_add_u64 v[14:15], v[42:43], 0, v[64:65]
	ds_bpermute_b32 v248, v250, v14
	ds_bpermute_b32 v249, v250, v15
	s_waitcnt lgkmcnt(0)
	global_store_dwordx2 v[248:249], v[12:13], off
	v_pk_mul_f32 v[4:5], v[4:5], v[50:51] op_sel_hi:[1,0]
	s_waitcnt vmcnt(7)
	v_lshlrev_b32_e32 v12, 16, v52
	v_and_b32_e32 v13, 0xffff0000, v52
	v_pk_mul_f32 v[6:7], v[6:7], v[50:51] op_sel_hi:[1,0]
	v_pk_mul_f32 v[4:5], v[4:5], v[12:13]
	v_lshlrev_b32_e32 v12, 16, v53
	v_and_b32_e32 v13, 0xffff0000, v53
	v_pk_mul_f32 v[6:7], v[6:7], v[12:13]
	v_cvt_pk_bf16_f32 v4, v4, v5
	v_cvt_pk_bf16_f32 v5, v6, v7
	v_pk_mul_f32 v[6:7], v[8:9], v[50:51] op_sel_hi:[1,0]
	s_waitcnt vmcnt(6)
	v_lshlrev_b32_e32 v8, 16, v54
	v_and_b32_e32 v9, 0xffff0000, v54
	global_store_dwordx2 v[248:249], v[4:5], off offset:32
	v_pk_mul_f32 v[4:5], v[10:11], v[50:51] op_sel_hi:[1,0]
	v_pk_mul_f32 v[6:7], v[6:7], v[8:9]
	v_lshlrev_b32_e32 v8, 16, v55
	v_and_b32_e32 v9, 0xffff0000, v55
	v_pk_mul_f32 v[4:5], v[4:5], v[8:9]
	v_cvt_pk_bf16_f32 v6, v6, v7
	v_cvt_pk_bf16_f32 v7, v4, v5
	v_pk_mul_f32 v[0:1], v[0:1], v[50:51] op_sel_hi:[1,0]
	s_waitcnt vmcnt(6)
	v_lshlrev_b32_e32 v4, 16, v44
	v_and_b32_e32 v5, 0xffff0000, v44
	v_pk_mul_f32 v[2:3], v[2:3], v[50:51] op_sel_hi:[1,0]
	v_pk_mul_f32 v[0:1], v[0:1], v[4:5]
	v_lshlrev_b32_e32 v4, 16, v45
	v_and_b32_e32 v5, 0xffff0000, v45
	v_pk_mul_f32 v[2:3], v[2:3], v[4:5]
	v_cvt_pk_bf16_f32 v0, v0, v1
	v_cvt_pk_bf16_f32 v1, v2, v3
	global_store_dwordx2 v[248:249], v[6:7], off offset:64
	global_store_dwordx2 v[248:249], v[0:1], off offset:96
	s_barrier
	s_cbranch_scc1 .LBB0_921
